# GEMM1 epilogue addressing: one 32-bit byte offset against the ux base (saddr form) + literal row-group adds + immediate column-half offset instead of sixteen 64-bit address computations
# baseline (speedup 1.0000x reference)
.LBB0_292:
	v_lshl_or_b32 v140, s78, 8, v143
	v_lshl_add_u32 v145, s79, 8, v129
	v_mul_u32_u24_e32 v141, 0x1200, v145
	v_lshl_add_u32 v141, v140, 1, v141
	v_cvt_pk_bf16_f32 v156, v124, v125
	v_cvt_pk_bf16_f32 v157, v126, v127
	v_cvt_pk_bf16_f32 v158, v120, v121
	v_cvt_pk_bf16_f32 v159, v122, v123
	global_store_dwordx4 v141, v[156:159], s[36:37] sc1
	s_nop 1
	v_cvt_pk_bf16_f32 v160, v116, v117
	v_cvt_pk_bf16_f32 v161, v118, v119
	v_cvt_pk_bf16_f32 v162, v108, v109
	v_cvt_pk_bf16_f32 v163, v110, v111
	global_store_dwordx4 v141, v[160:163], s[36:37] offset:256 sc1
	s_nop 1
	v_cvt_pk_bf16_f32 v164, v112, v113
	v_cvt_pk_bf16_f32 v165, v114, v115
	v_cvt_pk_bf16_f32 v166, v104, v105
	v_cvt_pk_bf16_f32 v167, v106, v107
	v_add_u32_e32 v146, 0x12000, v141
	global_store_dwordx4 v146, v[164:167], s[36:37] sc1
	s_nop 1
	v_cvt_pk_bf16_f32 v168, v100, v101
	v_cvt_pk_bf16_f32 v169, v102, v103
	v_cvt_pk_bf16_f32 v170, v92, v93
	v_cvt_pk_bf16_f32 v171, v94, v95
	global_store_dwordx4 v146, v[168:171], s[36:37] offset:256 sc1
	s_nop 1
	v_cvt_pk_bf16_f32 v172, v96, v97
	v_cvt_pk_bf16_f32 v173, v98, v99
	v_cvt_pk_bf16_f32 v174, v88, v89
	v_cvt_pk_bf16_f32 v175, v90, v91
	v_add_u32_e32 v146, 0x24000, v141
	global_store_dwordx4 v146, v[172:175], s[36:37] sc1
	s_nop 1
	v_cvt_pk_bf16_f32 v176, v84, v85
	v_cvt_pk_bf16_f32 v177, v86, v87
	v_cvt_pk_bf16_f32 v178, v76, v77
	v_cvt_pk_bf16_f32 v179, v78, v79
	global_store_dwordx4 v146, v[176:179], s[36:37] offset:256 sc1
	s_nop 1
	v_cvt_pk_bf16_f32 v180, v80, v81
	v_cvt_pk_bf16_f32 v181, v82, v83
	v_cvt_pk_bf16_f32 v182, v72, v73
	v_cvt_pk_bf16_f32 v183, v74, v75
	v_add_u32_e32 v146, 0x36000, v141
	global_store_dwordx4 v146, v[180:183], s[36:37] sc1
	s_nop 1
	v_cvt_pk_bf16_f32 v184, v68, v69
	v_cvt_pk_bf16_f32 v185, v70, v71
	v_cvt_pk_bf16_f32 v186, v64, v65
	v_cvt_pk_bf16_f32 v187, v66, v67
	global_store_dwordx4 v146, v[184:187], s[36:37] offset:256 sc1
	s_nop 1
	v_cvt_pk_bf16_f32 v156, v60, v61
	v_cvt_pk_bf16_f32 v157, v62, v63
	v_cvt_pk_bf16_f32 v158, v56, v57
	v_cvt_pk_bf16_f32 v159, v58, v59
	v_add_u32_e32 v146, 0x90000, v141
	global_store_dwordx4 v146, v[156:159], s[36:37] sc1
	s_nop 1
	v_cvt_pk_bf16_f32 v160, v52, v53
	v_cvt_pk_bf16_f32 v161, v54, v55
	v_cvt_pk_bf16_f32 v162, v44, v45
	v_cvt_pk_bf16_f32 v163, v46, v47
	global_store_dwordx4 v146, v[160:163], s[36:37] offset:256 sc1
	s_nop 1
	v_cvt_pk_bf16_f32 v164, v48, v49
	v_cvt_pk_bf16_f32 v165, v50, v51
	v_cvt_pk_bf16_f32 v166, v40, v41
	v_cvt_pk_bf16_f32 v167, v42, v43
	v_add_u32_e32 v146, 0xa2000, v141
	global_store_dwordx4 v146, v[164:167], s[36:37] sc1
	s_nop 1
	v_cvt_pk_bf16_f32 v168, v36, v37
	v_cvt_pk_bf16_f32 v169, v38, v39
	v_cvt_pk_bf16_f32 v170, v28, v29
	v_cvt_pk_bf16_f32 v171, v30, v31
	global_store_dwordx4 v146, v[168:171], s[36:37] offset:256 sc1
	s_nop 1
	v_cvt_pk_bf16_f32 v172, v32, v33
	v_cvt_pk_bf16_f32 v173, v34, v35
	v_cvt_pk_bf16_f32 v174, v24, v25
	v_cvt_pk_bf16_f32 v175, v26, v27
	v_add_u32_e32 v146, 0xb4000, v141
	global_store_dwordx4 v146, v[172:175], s[36:37] sc1
	s_nop 1
	v_cvt_pk_bf16_f32 v176, v20, v21
	v_cvt_pk_bf16_f32 v177, v22, v23
	v_cvt_pk_bf16_f32 v178, v12, v13
	v_cvt_pk_bf16_f32 v179, v14, v15
	global_store_dwordx4 v146, v[176:179], s[36:37] offset:256 sc1
	s_nop 1
	v_cvt_pk_bf16_f32 v180, v16, v17
	v_cvt_pk_bf16_f32 v181, v18, v19
	v_cvt_pk_bf16_f32 v182, v8, v9
	v_cvt_pk_bf16_f32 v183, v10, v11
	v_add_u32_e32 v146, 0xc6000, v141
	global_store_dwordx4 v146, v[180:183], s[36:37] sc1
	s_nop 1
	v_cvt_pk_bf16_f32 v184, v4, v5
	v_cvt_pk_bf16_f32 v185, v6, v7
	v_cvt_pk_bf16_f32 v186, v0, v1
	v_cvt_pk_bf16_f32 v187, v2, v3
	s_andn2_b64 vcc, exec, s[40:41]
	global_store_dwordx4 v146, v[184:187], s[36:37] offset:256 sc1
	s_nop 1
	s_mov_b64 s[40:41], -1
	s_cbranch_vccnz .LBB0_285
	s_andn2_b64 vcc, exec, s[34:35]
	s_cbranch_vccnz .LBB0_284
	s_branch .LBB0_284
